# GQA odd step: row-sum add chain spread over the QK gaps; GQA unit prologue requests K(2)/V(1) together with the first tiles
# speedup vs baseline: 1.0023x; 1.0004x over previous
; template <int DK>
; __device__ __forceinline__ void attn_unit(LAS unsigned char* lds, const bf16_t* Qp, int qpitch, const bf16_t* Kp, int kpitch, const bf16_t* Vp, int vpitch, bf16_t* Op, int nt) {
;     ...
;     int tid_ = threadIdx.x; asm volatile("" : "+v"(tid_));
;     const int tid = tid_, lane = tid & 63, wid = tid >> 6, r32 = lane & 31, hi = lane >> 5;
;     bf16x8 qf[NDS];
;     {
;         const bf16_t* qrow = Qp + (size_t)(wid * 32 + r32) * qpitch + 8 * hi;
; #pragma unroll
;         for (int ds = 0; ds < NDS; ++ds) qf[ds] = *(const bf16x8*)(qrow + ds * 16);
;     }
;     const int kr0 = tid / KCH, kc0 = tid % KCH;
;     const int c1 = tid + NTHREADS; const bool has1 = (DK == 96) && (c1 < 64 * KCH);
;     const int kr1 = has1 ? c1 / KCH : 0, kc1 = has1 ? c1 % KCH : 0;
;     const int vd = tid >> 3, vc = tid & 7;
;     const bf16_t* kg0 = Kp + (size_t)kr0 * kpitch + kc0 * 8;
;     const bf16_t* kg1 = Kp + (size_t)kr1 * kpitch + kc1 * 8;
;     const bf16_t* vg = Vp + (size_t)vd * vpitch + vc * 8;
;     const size_t kstep = (size_t)64 * kpitch, vstep = (size_t)64 * vpitch;
;     const int kl0 = kr0 * KSTR + kc0 * 16, kl1 = kr1 * KSTR + kc1 * 16, vl = vd * VSTR + vc * 16;
;     const int aoffk = r32 * KSTR + hi * 16;
;     const int aoffv = (4 * hi + ((lane & 15) >> 2)) * VSTR + (((lane >> 4) & 1) * 16 + (lane & 3) * 4) * 2;
;     {
;         const u32x4 a0 = *(const u32x4*)kg0, b0 = *(const u32x4*)(kg0 + kstep), v0 = *(const u32x4*)vg;
;         u32x4 a1 = {0u, 0u, 0u, 0u}, b1 = {0u, 0u, 0u, 0u};
;         if (has1) { a1 = *(const u32x4*)kg1; b1 = *(const u32x4*)(kg1 + kstep); }
;         *(LAS u32x4*)(lds + kl0) = a0; *(LAS u32x4*)(lds + KBUF + kl0) = b0; *(LAS u32x4*)(lds + 2 * KBUF + vl) = v0;
;         if (has1) { *(LAS u32x4*)(lds + kl1) = a1; *(LAS u32x4*)(lds + KBUF + kl1) = b1; }
;     }
;     u32x4 rkA0 = {0u, 0u, 0u, 0u}, rkA1 = {0u, 0u, 0u, 0u}, rvA = {0u, 0u, 0u, 0u}, rkB0, rkB1 = {0u, 0u, 0u, 0u}, rvB;
;     rkB0 = *(const u32x4*)(kg0 + 2 * kstep); if (has1) rkB1 = *(const u32x4*)(kg1 + 2 * kstep); rvB = *(const u32x4*)(vg + vstep);
;     __syncthreads();
;     f32x16 o0, o1, cA0, cA1, cB0, cB1;
; #pragma unroll
;     for (int i = 0; i < 16; ++i) { o0[i] = 0.f; o1[i] = 0.f; cA0[i] = 0.f; cA1[i] = 0.f; }
; #pragma unroll
;     for (int ds = 0; ds < NDS; ++ds) {
;         const bf16x8 a0 = *(const LAS bf16x8*)(lds + aoffk + ds * 32);
.LBB0_777:
	s_and_b64 vcc, exec, s[16:17]
	s_cbranch_vccz .LBB0_740
	v_mov_b32_e32 v8, v174
	s_movk_i32 s16, 0xffe0
	v_ashrrev_i32_e32 v0, 1, v8
	v_bfe_u32 v9, v8, 5, 1
	v_bfi_b32 v114, s16, v0, v8
	v_mov_b64_e32 v[0:1], s[14:15]
	s_movk_i32 s14, 0x300
	v_mad_i64_i32 v[0:1], s[14:15], v114, s14, v[0:1]
	v_lshlrev_b32_e32 v96, 4, v9
	v_lshl_add_u64 v[0:1], v[0:1], 0, v[96:97]
	global_load_dwordx4 v[76:79], v[0:1], off
	global_load_dwordx4 v[72:75], v[0:1], off offset:32
	global_load_dwordx4 v[68:71], v[0:1], off offset:64
	global_load_dwordx4 v[64:67], v[0:1], off offset:96
	v_ashrrev_i32_e32 v0, 31, v8
	v_lshrrev_b32_e32 v0, 29, v0
	v_add_u32_e32 v1, v8, v0
	v_ashrrev_i32_e32 v0, 3, v1
	v_and_b32_e32 v1, -8, v1
	v_sub_u32_e32 v10, v8, v1
	v_ashrrev_i32_e32 v2, 3, v8
	v_ashrrev_i32_e32 v1, 31, v0
	v_lshlrev_b32_e32 v6, 3, v10
	v_lshlrev_b64 v[36:37], 8, v[0:1]
	v_ashrrev_i32_e32 v7, 31, v6
	v_ashrrev_i32_e32 v3, 31, v2
	v_lshl_add_u64 v[4:5], s[12:13], 0, v[36:37]
	v_lshlrev_b64 v[38:39], 1, v[6:7]
	v_lshlrev_b64 v[32:33], 8, v[2:3]
	v_lshlrev_b32_e32 v1, 4, v8
	v_lshl_add_u64 v[120:121], v[4:5], 0, v[38:39]
	v_lshl_add_u64 v[4:5], s[10:11], 0, v[32:33]
	v_and_b32_e32 v34, 0x70, v1
	v_mov_b32_e32 v35, v97
	s_movk_i32 s12, 0x90
	s_movk_i32 s10, 0xc0
	v_mul_lo_u32 v0, v0, s12
	v_mad_u64_u32 v[12:13], s[10:11], v2, s10, v[34:35]
	v_lshl_add_u32 v15, v10, 4, v0
	v_bfe_u32 v0, v8, 2, 2
	s_movk_i32 s10, 0x4000
	v_lshl_add_u64 v[118:119], v[4:5], 0, v[34:35]
	v_lshl_or_b32 v13, v9, 2, v0
	v_and_b32_e32 v0, 16, v8
	v_lshlrev_b32_e32 v1, 2, v8
	v_add_co_u32_e32 v4, vcc, s10, v120
	v_and_or_b32 v48, v1, 12, v0
	global_load_dwordx4 v[0:3], v[120:121], off
	v_addc_co_u32_e32 v5, vcc, 0, v121, vcc
	v_and_b32_e32 v14, 31, v8
	v_lshlrev_b32_e32 v116, 3, v9
	global_load_dwordx4 v[4:7], v[4:5], off
	s_nop 0
	global_load_dwordx4 v[8:11], v[118:119], off
	v_add_co_u32_e32 v40, vcc, 0x8000, v120
	s_nop 1
	v_addc_co_u32_e32 v41, vcc, 0, v121, vcc
	global_load_dwordx4 v[80:83], v[40:41], off
	v_add_co_u32_e32 v40, vcc, 0x4000, v118
	s_nop 1
	v_addc_co_u32_e32 v41, vcc, 0, v119, vcc
	global_load_dwordx4 v[84:87], v[40:41], off
	v_add_u32_e32 v130, 0, v15
	s_mov_b32 s11, 0x8000
	v_add_u32_e32 v117, 0, v12
	v_mul_u32_u24_e32 v49, 0xc0, v13
	v_mov_b32_e32 v172, 0
	v_ashrrev_i32_e32 v115, 31, v114
	s_waitcnt vmcnt(4)
	ds_write_b128 v130, v[0:3]
	s_waitcnt vmcnt(3)
	ds_write_b128 v130, v[4:7] offset:13312
	s_waitcnt vmcnt(2)
	ds_write_b128 v117, v[8:11] offset:26624
	s_mov_b32 s10, -2
	s_nop 0
	v_mad_u32_u24 v0, v14, s12, v96
	v_add_u32_e32 v131, 0, v0
	s_waitcnt lgkmcnt(0)
	s_barrier
	ds_read_b128 v[16:19], v131 offset:4608
	ds_read_b128 v[0:3], v131
	ds_read_b128 v[40:43], v131 offset:32
	s_waitcnt lgkmcnt(1)
	v_mfma_f32_32x32x16_bf16 v[0:15], v[0:3], v[76:79], 0
	ds_read_b128 v[44:47], v131 offset:4640
	v_mfma_f32_32x32x16_bf16 v[16:31], v[16:19], v[76:79], 0
	s_waitcnt lgkmcnt(1)
	v_mfma_f32_32x32x16_bf16 v[0:15], v[40:43], v[72:75], v[0:15]
	s_waitcnt lgkmcnt(0)
	v_mfma_f32_32x32x16_bf16 v[16:31], v[44:47], v[72:75], v[16:31]
	ds_read_b128 v[40:43], v131 offset:64
	ds_read_b128 v[44:47], v131 offset:4672
	s_waitcnt lgkmcnt(1)
	v_mfma_f32_32x32x16_bf16 v[0:15], v[40:43], v[68:71], v[0:15]
	s_waitcnt lgkmcnt(0)
	v_mfma_f32_32x32x16_bf16 v[16:31], v[44:47], v[68:71], v[16:31]
	ds_read_b128 v[40:43], v131 offset:96
	ds_read_b128 v[44:47], v131 offset:4704
	s_waitcnt lgkmcnt(0)
	s_barrier
	v_mfma_f32_32x32x16_bf16 v[0:15], v[40:43], v[64:67], v[0:15]
	v_mfma_f32_32x32x16_bf16 v[16:31], v[44:47], v[64:67], v[16:31]
	s_nop 10
	v_exp_f32_e32 v146, v0
	v_lshl_or_b32 v0, v48, 1, v49
	v_exp_f32_e32 v148, v1
	v_add_u32_e32 v96, 0, v0
	v_lshl_add_u64 v[0:1], s[70:71], 0, v[36:37]
	v_exp_f32_e32 v158, v2
	v_exp_f32_e32 v159, v3
	v_exp_f32_e32 v132, v16
	v_exp_f32_e32 v133, v17
	v_exp_f32_e32 v134, v18
	v_exp_f32_e32 v135, v19
	v_exp_f32_e32 v160, v4
	v_exp_f32_e32 v136, v20
	v_exp_f32_e32 v162, v5
	v_exp_f32_e32 v137, v21
	v_exp_f32_e32 v164, v6
	v_exp_f32_e32 v139, v22
	v_exp_f32_e32 v166, v7
	v_exp_f32_e32 v141, v23
	v_exp_f32_e32 v161, v8
	v_exp_f32_e32 v138, v24
	v_exp_f32_e32 v163, v9
	v_exp_f32_e32 v140, v25
	v_exp_f32_e32 v165, v10
	v_exp_f32_e32 v142, v26
	v_exp_f32_e32 v168, v11
	v_exp_f32_e32 v143, v27
	v_exp_f32_e32 v167, v12
	v_exp_f32_e32 v144, v28
	v_exp_f32_e32 v169, v13
	v_exp_f32_e32 v145, v29
	v_exp_f32_e32 v170, v14
	v_exp_f32_e32 v147, v30
	v_exp_f32_e32 v171, v15
	v_exp_f32_e32 v149, v31
	v_lshl_add_u64 v[0:1], v[0:1], 0, v[38:39]
	v_lshl_add_u64 v[122:123], s[50:51], 0, v[0:1]
	v_lshl_add_u64 v[0:1], s[70:71], 0, v[32:33]
	v_lshl_add_u64 v[0:1], v[0:1], 0, v[34:35]
	v_lshl_add_u64 v[124:125], s[50:51], 0, v[0:1]
	v_mov_b32_e32 v0, 0
	v_mov_b32_e32 v1, v172
	v_mov_b32_e32 v2, v172
	v_mov_b32_e32 v3, v172
	v_mov_b32_e32 v4, v172
	v_mov_b32_e32 v5, v172
	v_mov_b32_e32 v6, v172
	v_mov_b32_e32 v7, v172
	v_mov_b32_e32 v8, v172
	v_mov_b32_e32 v9, v172
	v_mov_b32_e32 v10, v172
	v_mov_b32_e32 v11, v172
	v_mov_b32_e32 v12, v172
	v_mov_b32_e32 v13, v172
	v_mov_b32_e32 v14, v172
	v_mov_b32_e32 v15, v172
	v_mov_b32_e32 v16, 0
	v_mov_b32_e32 v17, v172
	v_mov_b32_e32 v18, v172
	v_mov_b32_e32 v19, v172
	v_mov_b32_e32 v20, v172
	v_mov_b32_e32 v21, v172
	v_mov_b32_e32 v22, v172
	v_mov_b32_e32 v23, v172
	v_mov_b32_e32 v24, v172
	v_mov_b32_e32 v25, v172
	v_mov_b32_e32 v26, v172
	v_mov_b32_e32 v27, v172
	v_mov_b32_e32 v28, v172
	v_mov_b32_e32 v29, v172
	v_mov_b32_e32 v30, v172
	v_mov_b32_e32 v31, v172
	s_waitcnt vmcnt(0)
	ds_write_b128 v130, v[80:83]
	ds_read_b128 v[216:219], v131 offset:17920
	ds_read_b128 v[220:223], v131 offset:13312
	ds_read_b128 v[224:227], v131 offset:13344
	ds_read_b128 v[228:231], v131 offset:17952
	ds_read_b128 v[236:239], v131 offset:13376
	ds_read_b128 v[240:243], v131 offset:17984
	ds_read_b128 v[244:247], v131 offset:13408
	ds_read_b128 v[248:251], v131 offset:18016
	v_add_co_u32_e32 v32, vcc, 0xc000, v120
	s_nop 1
	v_addc_co_u32_e32 v33, vcc, 0, v121, vcc
	s_waitcnt lgkmcnt(8)
	global_load_dwordx4 v[80:83], v[32:33], off
	v_add_co_u32_e32 v32, vcc, 0x4000, v118
	s_nop 1
	v_addc_co_u32_e32 v33, vcc, 0, v119, vcc
	global_load_dwordx4 v[84:87], v[32:33], off
	s_waitcnt lgkmcnt(0)
	s_barrier
; #define LAS __attribute__((address_space(3)))
; template <int DK, int PAR, bool HASNEXT, bool LDK, bool LDV, bool STK> ...
;     ...
;     LAS unsigned char* Kb = lds + ((PAR ^ 1) * A::KBUF);
;     LAS unsigned char* Vb = lds + 2 * A::KBUF + PAR * A::VBUF;
;     __builtin_amdgcn_s_setprio(1);
;     if (LDK) { ldk0 = *(const u32x4*)(kg0 + (size_t)(t + 3) * kstep); if (has1) ldk1 = *(const u32x4*)(kg1 + (size_t)(t + 3) * kstep); }
;     if (LDV) ldv = *(const u32x4*)(vg + (size_t)(t + 2) * vstep);
;     bf16x8 kf[A::NDS][2];
;     if (HASNEXT) {
; #pragma unroll
;         for (int ds = 0; ds < A::NDS; ++ds) {
;             kf[ds][0] = *(const LAS bf16x8*)(Kb + aoffk + ds * 32);
;             kf[ds][1] = *(const LAS bf16x8*)(Kb + aoffk + 32 * A::KSTR + ds * 32);
;         }
;     }
;     s16x4 vlo[4][2], vhi[4][2];
; #pragma unroll
;     for (int j = 0; j < 2; ++j) {
;         vlo[j][0] = vtr(Vb + aoffv + j * 16 * A::VSTR); vhi[j][0] = vtr(Vb + aoffv + (j * 16 + 8) * A::VSTR);
;         vlo[j][1] = vtr(Vb + aoffv + j * 16 * A::VSTR + 64); vhi[j][1] = vtr(Vb + aoffv + (j * 16 + 8) * A::VSTR + 64);
;     }
;     if (HASNEXT) {
;         f32x16 z;
; #pragma unroll
;         for (int i = 0; i < 16; ++i) z[i] = 0.f;
; #pragma unroll
;         for (int ds = 0; ds < A::NDS; ++ds) {
;             N0 = __builtin_amdgcn_mfma_f32_32x32x16_bf16(kf[ds][0], qf[ds], ds == 0 ? z : N0, 0, 0, 0);
;             N1 = __builtin_amdgcn_mfma_f32_32x32x16_bf16(kf[ds][1], qf[ds], ds == 0 ? z : N1, 0, 0, 0);
;         }
;     }
; #pragma unroll
;     for (int i = 0; i < 16; ++i) { l += C0[i]; l += C1[i]; }
;     bf16x8 pb[4];
;     { u32x4 w;
;       w.x = pk2(C0[0], C0[1]); w.y = pk2(C0[2], C0[3]); w.z = pk2(C0[4], C0[5]); w.w = pk2(C0[6], C0[7]); pb[0] = __builtin_bit_cast(bf16x8, w);
;       w.x = pk2(C0[8], C0[9]); w.y = pk2(C0[10], C0[11]); w.z = pk2(C0[12], C0[13]); w.w = pk2(C0[14], C0[15]); pb[1] = __builtin_bit_cast(bf16x8, w);
;       w.x = pk2(C1[0], C1[1]); w.y = pk2(C1[2], C1[3]); w.z = pk2(C1[4], C1[5]); w.w = pk2(C1[6], C1[7]); pb[2] = __builtin_bit_cast(bf16x8, w);
;       w.x = pk2(C1[8], C1[9]); w.y = pk2(C1[10], C1[11]); w.z = pk2(C1[12], C1[13]); w.w = pk2(C1[14], C1[15]); pb[3] = __builtin_bit_cast(bf16x8, w); }
;     if (HASNEXT) {
;         constexpr int VPER = (DK == 64) ? 6 : 4;
; #pragma unroll
.LBB0_779:
	s_setprio 1
	s_mov_b32 s11, 0x23a30000
	ds_read_b64_tr_b16 v[110:111], v96 offset:26624
	v_mfma_f32_32x32x16_bf16 v[48:63], v[216:219], v[76:79], 0
	v_lshl_add_u64 v[126:127], v[122:123], 0, s[8:9]
	v_add_co_u32_e32 v32, vcc, s11, v126
	v_lshl_add_u64 v[128:129], v[124:125], 0, s[8:9]
	s_nop 0
	v_addc_co_u32_e32 v33, vcc, 0, v127, vcc
	s_mov_b32 s11, 0x24aa8000
	global_load_dwordx4 v[88:91], v[32:33], off
	v_add_co_u32_e32 v32, vcc, s11, v128
	ds_read_b64_tr_b16 v[112:113], v96 offset:28160
	s_nop 0
	v_addc_co_u32_e32 v33, vcc, 0, v129, vcc
	global_load_dwordx4 v[92:95], v[32:33], off
	v_mfma_f32_32x32x16_bf16 v[32:47], v[220:223], v[76:79], 0
	v_add_f32_e32 v150, v146, v172
	v_add_f32_e32 v150, v132, v150
	v_add_f32_e32 v150, v148, v150
	v_add_f32_e32 v150, v133, v150
	v_add_f32_e32 v150, v158, v150
	v_add_f32_e32 v150, v134, v150
	ds_read_b64_tr_b16 v[106:107], v96 offset:26688
	v_mfma_f32_32x32x16_bf16 v[32:47], v[224:227], v[72:75], v[32:47]
	v_add_f32_e32 v150, v159, v150
	v_add_f32_e32 v150, v135, v150
	v_add_f32_e32 v150, v160, v150
	v_add_f32_e32 v150, v136, v150
	v_add_f32_e32 v150, v162, v150
	v_add_f32_e32 v150, v137, v150
	ds_read_b64_tr_b16 v[108:109], v96 offset:28224
	v_mfma_f32_32x32x16_bf16 v[48:63], v[228:231], v[72:75], v[48:63]
	s_waitcnt vmcnt(3)
	ds_write_b128 v130, v[80:83] offset:13312
	s_waitcnt vmcnt(2)
	ds_write_b128 v117, v[84:87] offset:38912
	v_add_f32_e32 v150, v164, v150
	v_add_f32_e32 v150, v139, v150
	v_add_f32_e32 v150, v166, v150
	v_add_f32_e32 v150, v141, v150
	v_add_f32_e32 v150, v161, v150
	v_add_f32_e32 v150, v138, v150
	ds_read_b64_tr_b16 v[102:103], v96 offset:29696
	v_mfma_f32_32x32x16_bf16 v[32:47], v[236:239], v[68:71], v[32:47]
	v_add_f32_e32 v150, v163, v150
	v_add_f32_e32 v150, v140, v150
	v_add_f32_e32 v150, v165, v150
	v_add_f32_e32 v150, v142, v150
	v_add_f32_e32 v150, v168, v150
	v_add_f32_e32 v150, v143, v150
	ds_read_b64_tr_b16 v[104:105], v96 offset:31232
	v_mfma_f32_32x32x16_bf16 v[48:63], v[240:243], v[68:71], v[48:63]
	v_add_f32_e32 v150, v167, v150
	v_add_f32_e32 v150, v144, v150
	v_add_f32_e32 v150, v169, v150
	v_add_f32_e32 v150, v145, v150
	ds_read_b64_tr_b16 v[98:99], v96 offset:29760
	ds_read_b64_tr_b16 v[100:101], v96 offset:31296
	v_add_f32_e32 v150, v170, v150
	v_add_f32_e32 v150, v147, v150
	v_mfma_f32_32x32x16_bf16 v[32:47], v[244:247], v[64:67], v[32:47]
	v_add_f32_e32 v150, v171, v150
	v_add_f32_e32 v152, v149, v150
	v_cvt_pk_bf16_f32 v182, v146, v148
	v_cvt_pk_bf16_f32 v183, v158, v159
	v_cvt_pk_bf16_f32 v184, v160, v162
	v_cvt_pk_bf16_f32 v185, v164, v166
	v_mfma_f32_32x32x16_bf16 v[48:63], v[248:251], v[64:67], v[48:63]
	v_cvt_pk_bf16_f32 v158, v161, v163
	v_cvt_pk_bf16_f32 v159, v165, v168
	v_cvt_pk_bf16_f32 v160, v167, v169
	v_cvt_pk_bf16_f32 v161, v170, v171
	v_cvt_pk_bf16_f32 v132, v132, v133
	v_cvt_pk_bf16_f32 v133, v134, v135
	v_cvt_pk_bf16_f32 v134, v136, v137
	v_cvt_pk_bf16_f32 v135, v139, v141
	v_cvt_pk_bf16_f32 v136, v138, v140
	v_cvt_pk_bf16_f32 v137, v142, v143
	v_cvt_pk_bf16_f32 v138, v144, v145
	v_cvt_pk_bf16_f32 v139, v147, v149
	s_waitcnt lgkmcnt(8)
	v_mfma_f32_32x32x16_bf16 v[16:31], v[110:113], v[182:185], v[16:31]
	ds_read_b64_tr_b16 v[110:111], v96 offset:32832
	ds_read_b64_tr_b16 v[112:113], v96 offset:34368
	ds_read_b64_tr_b16 v[140:141], v96 offset:35904
	ds_read_b64_tr_b16 v[142:143], v96 offset:37440
	v_exp_f32_e32 v162, v51
	v_exp_f32_e32 v163, v36
	v_exp_f32_e32 v164, v52
	s_waitcnt lgkmcnt(10)
	v_mfma_f32_32x32x16_bf16 v[0:15], v[106:109], v[182:185], v[0:15]
	ds_read_b64_tr_b16 v[106:107], v96 offset:32768
	ds_read_b64_tr_b16 v[108:109], v96 offset:34304
	v_exp_f32_e32 v165, v37
	v_exp_f32_e32 v166, v53
	v_exp_f32_e32 v167, v38
	v_exp_f32_e32 v168, v54
	v_exp_f32_e32 v169, v39
	s_waitcnt lgkmcnt(8)
	v_mfma_f32_32x32x16_bf16 v[16:31], v[102:105], v[158:161], v[16:31]
	ds_read_b64_tr_b16 v[102:103], v96 offset:35840
	ds_read_b64_tr_b16 v[104:105], v96 offset:37376
	v_exp_f32_e32 v170, v55
	v_exp_f32_e32 v171, v40
	v_exp_f32_e32 v153, v32
	v_exp_f32_e32 v154, v48
	v_exp_f32_e32 v155, v33
	s_waitcnt lgkmcnt(8)
	v_mfma_f32_32x32x16_bf16 v[0:15], v[98:101], v[158:161], v[0:15]
	ds_read_b128 v[216:219], v131 offset:4608
	ds_read_b128 v[220:223], v131
	v_exp_f32_e32 v158, v49
	v_exp_f32_e32 v159, v34
	v_exp_f32_e32 v160, v50
	v_exp_f32_e32 v161, v35
	v_exp_f32_e32 v173, v56
	v_exp_f32_e32 v180, v41
	v_exp_f32_e32 v181, v57
	s_waitcnt lgkmcnt(4)
	v_mfma_f32_32x32x16_bf16 v[16:31], v[106:109], v[132:135], v[16:31]
	ds_read_b128 v[224:227], v131 offset:32
	ds_read_b128 v[228:231], v131 offset:64
	v_exp_f32_e32 v182, v42
	v_exp_f32_e32 v183, v58
	v_exp_f32_e32 v184, v43
	v_exp_f32_e32 v185, v59
	v_exp_f32_e32 v186, v44
	v_exp_f32_e32 v187, v60
	v_exp_f32_e32 v188, v45
	v_mfma_f32_32x32x16_bf16 v[0:15], v[110:113], v[132:135], v[0:15]
	ds_read_b128 v[236:239], v131 offset:96
	ds_read_b128 v[240:243], v131 offset:4640
	v_exp_f32_e32 v189, v61
	v_exp_f32_e32 v190, v46
	v_exp_f32_e32 v191, v62
	v_exp_f32_e32 v192, v47
	v_exp_f32_e32 v193, v63
	s_waitcnt lgkmcnt(6)
	v_mfma_f32_32x32x16_bf16 v[16:31], v[102:105], v[136:139], v[16:31]
	ds_read_b128 v[244:247], v131 offset:4672
	ds_read_b128 v[248:251], v131 offset:4704
	v_mfma_f32_32x32x16_bf16 v[0:15], v[140:143], v[136:139], v[0:15]
	s_setprio 0
	s_waitcnt lgkmcnt(0)
	s_barrier
; __device__ __forceinline__ unsigned pk2(float lo, float hi) { f32x2_t v = {lo, hi}; bf16x2_t b = __builtin_convertvector(v, bf16x2_t); return __builtin_bit_cast(unsigned, b); }
; template <int DK, int PAR, bool HASNEXT, bool LDK, bool LDV, bool STK> ...
;     ...
; #pragma unroll
;     for (int i = 0; i < 16; ++i) { l += C0[i]; l += C1[i]; }
;     bf16x8 pb[4];
;     { u32x4 w;
;       w.x = pk2(C0[0], C0[1]); w.y = pk2(C0[2], C0[3]); w.z = pk2(C0[4], C0[5]); w.w = pk2(C0[6], C0[7]); pb[0] = __builtin_bit_cast(bf16x8, w);
;       w.x = pk2(C0[8], C0[9]); w.y = pk2(C0[10], C0[11]); w.z = pk2(C0[12], C0[13]); w.w = pk2(C0[14], C0[15]); pb[1] = __builtin_bit_cast(bf16x8, w);
;       w.x = pk2(C1[0], C1[1]); w.y = pk2(C1[2], C1[3]); w.z = pk2(C1[4], C1[5]); w.w = pk2(C1[6], C1[7]); pb[2] = __builtin_bit_cast(bf16x8, w);
;       w.x = pk2(C1[8], C1[9]); w.y = pk2(C1[10], C1[11]); w.z = pk2(C1[12], C1[13]); w.w = pk2(C1[14], C1[15]); pb[3] = __builtin_bit_cast(bf16x8, w); }
	s_setprio 1
	s_mov_b32 s11, 0x23a34000
	ds_read_b64_tr_b16 v[110:111], v96 offset:38912
	ds_read_b64_tr_b16 v[112:113], v96 offset:40448
	v_mfma_f32_32x32x16_bf16 v[48:63], v[216:219], v[76:79], 0
	v_add_co_u32_e32 v32, vcc, s11, v126
	s_mov_b32 s11, 0x24aac000
	s_nop 0
	v_addc_co_u32_e32 v33, vcc, 0, v127, vcc
	global_load_dwordx4 v[80:83], v[32:33], off
	v_add_co_u32_e32 v32, vcc, s11, v128
	ds_read_b64_tr_b16 v[106:107], v96 offset:38976
	s_nop 0
	v_addc_co_u32_e32 v33, vcc, 0, v129, vcc
	global_load_dwordx4 v[84:87], v[32:33], off
	v_mfma_f32_32x32x16_bf16 v[32:47], v[220:223], v[76:79], 0
	ds_read_b64_tr_b16 v[108:109], v96 offset:40512
	ds_read_b64_tr_b16 v[102:103], v96 offset:41984
	ds_read_b64_tr_b16 v[104:105], v96 offset:43520
	ds_read_b64_tr_b16 v[98:99], v96 offset:42048
	ds_read_b64_tr_b16 v[100:101], v96 offset:43584
	v_add_f32_e32 v126, v153, v152
	v_add_f32_e32 v126, v154, v126
	v_add_f32_e32 v126, v155, v126
	v_add_f32_e32 v126, v158, v126
	v_add_f32_e32 v126, v159, v126
	v_mfma_f32_32x32x16_bf16 v[32:47], v[224:227], v[72:75], v[32:47]
	v_add_f32_e32 v126, v160, v126
	v_add_f32_e32 v126, v161, v126
	v_add_f32_e32 v126, v162, v126
	v_add_f32_e32 v126, v163, v126
	v_add_f32_e32 v126, v164, v126
	v_mfma_f32_32x32x16_bf16 v[32:47], v[228:231], v[68:71], v[32:47]
	s_waitcnt vmcnt(3)
	ds_write_b128 v130, v[88:91]
	s_waitcnt vmcnt(2)
	ds_write_b128 v117, v[92:95] offset:26624
	v_add_f32_e32 v126, v165, v126
	v_add_f32_e32 v126, v166, v126
	v_add_f32_e32 v126, v167, v126
	v_add_f32_e32 v126, v168, v126
	v_add_f32_e32 v126, v169, v126
	v_mfma_f32_32x32x16_bf16 v[32:47], v[236:239], v[64:67], v[32:47]
	v_add_f32_e32 v126, v170, v126
	v_add_f32_e32 v126, v171, v126
	v_add_f32_e32 v126, v173, v126
	v_add_f32_e32 v126, v180, v126
	v_cvt_pk_bf16_f32 v144, v164, v166
	v_cvt_pk_bf16_f32 v145, v168, v170
	v_cvt_pk_bf16_f32 v136, v186, v188
	v_cvt_pk_bf16_f32 v137, v190, v192
	v_mfma_f32_32x32x16_bf16 v[48:63], v[240:243], v[72:75], v[48:63]
	v_add_f32_e32 v126, v181, v126
	v_add_f32_e32 v126, v182, v126
	v_add_f32_e32 v126, v183, v126
	v_add_f32_e32 v126, v184, v126
	v_cvt_pk_bf16_f32 v134, v171, v180
	v_cvt_pk_bf16_f32 v135, v182, v184
	v_mfma_f32_32x32x16_bf16 v[48:63], v[244:247], v[68:71], v[48:63]
	v_add_f32_e32 v126, v185, v126
	v_add_f32_e32 v126, v186, v126
	v_add_f32_e32 v126, v187, v126
	v_add_f32_e32 v126, v188, v126
	v_cvt_pk_bf16_f32 v142, v154, v158
	v_cvt_pk_bf16_f32 v143, v160, v162
	v_mfma_f32_32x32x16_bf16 v[48:63], v[248:251], v[64:67], v[48:63]
	v_add_f32_e32 v126, v189, v126
	v_add_f32_e32 v126, v190, v126
	v_add_f32_e32 v126, v191, v126
	v_add_f32_e32 v126, v192, v126
	v_add_f32_e32 v172, v193, v126
	v_cvt_pk_bf16_f32 v126, v153, v155
	v_cvt_pk_bf16_f32 v127, v159, v161
	v_cvt_pk_bf16_f32 v128, v163, v165
	v_cvt_pk_bf16_f32 v129, v167, v169
	v_cvt_pk_bf16_f32 v182, v173, v181
	v_cvt_pk_bf16_f32 v183, v183, v185
	v_cvt_pk_bf16_f32 v184, v187, v189
	v_cvt_pk_bf16_f32 v185, v191, v193
	s_waitcnt lgkmcnt(8)
	v_mfma_f32_32x32x16_bf16 v[16:31], v[110:113], v[126:129], v[16:31]
	ds_read_b64_tr_b16 v[110:111], v96 offset:45120
	ds_read_b64_tr_b16 v[112:113], v96 offset:46656
	v_exp_f32_e32 v146, v32
	v_exp_f32_e32 v132, v48
	v_exp_f32_e32 v148, v33
	v_exp_f32_e32 v133, v49
	v_exp_f32_e32 v158, v34
	s_waitcnt lgkmcnt(8)
	v_mfma_f32_32x32x16_bf16 v[0:15], v[106:109], v[126:129], v[0:15]
	ds_read_b64_tr_b16 v[106:107], v96 offset:45056
	ds_read_b64_tr_b16 v[108:109], v96 offset:46592
	ds_read_b64_tr_b16 v[126:127], v96 offset:48192
	ds_read_b64_tr_b16 v[128:129], v96 offset:49728
	v_exp_f32_e32 v159, v35
	v_exp_f32_e32 v160, v36
	v_exp_f32_e32 v162, v37
	s_waitcnt lgkmcnt(10)
	v_mfma_f32_32x32x16_bf16 v[16:31], v[102:105], v[134:137], v[16:31]
	ds_read_b64_tr_b16 v[102:103], v96 offset:48128
	ds_read_b64_tr_b16 v[104:105], v96 offset:49664
	v_exp_f32_e32 v164, v38
	v_exp_f32_e32 v139, v54
	v_exp_f32_e32 v166, v39
	v_exp_f32_e32 v141, v55
	v_exp_f32_e32 v161, v40
	s_waitcnt lgkmcnt(10)
	v_mfma_f32_32x32x16_bf16 v[0:15], v[98:101], v[134:137], v[0:15]
	ds_read_b128 v[216:219], v131 offset:17920
	ds_read_b128 v[220:223], v131 offset:13312
	v_exp_f32_e32 v134, v50
	v_exp_f32_e32 v135, v51
	v_exp_f32_e32 v136, v52
	v_exp_f32_e32 v137, v53
	v_exp_f32_e32 v138, v56
	v_exp_f32_e32 v163, v41
	v_exp_f32_e32 v140, v57
	s_waitcnt lgkmcnt(6)
	v_mfma_f32_32x32x16_bf16 v[16:31], v[106:109], v[142:145], v[16:31]
	ds_read_b128 v[224:227], v131 offset:13344
	ds_read_b128 v[228:231], v131 offset:17952
	v_exp_f32_e32 v165, v42
	v_exp_f32_e32 v168, v43
	v_exp_f32_e32 v167, v44
	v_exp_f32_e32 v169, v45
	v_exp_f32_e32 v170, v46
	v_exp_f32_e32 v147, v62
	v_exp_f32_e32 v171, v47
	v_mfma_f32_32x32x16_bf16 v[0:15], v[110:113], v[142:145], v[0:15]
	ds_read_b128 v[236:239], v131 offset:13376
	ds_read_b128 v[240:243], v131 offset:17984
	v_exp_f32_e32 v142, v58
	v_exp_f32_e32 v143, v59
	v_exp_f32_e32 v144, v60
	v_exp_f32_e32 v145, v61
	v_exp_f32_e32 v149, v63
	s_waitcnt lgkmcnt(6)
	v_mfma_f32_32x32x16_bf16 v[16:31], v[102:105], v[182:185], v[16:31]
	ds_read_b128 v[244:247], v131 offset:13408
	ds_read_b128 v[248:251], v131 offset:18016
	v_mfma_f32_32x32x16_bf16 v[0:15], v[126:129], v[182:185], v[0:15]
	s_setprio 0
	s_waitcnt lgkmcnt(0)
	s_barrier
	s_add_i32 s10, s10, 2
	v_lshl_add_u64 v[122:123], v[122:123], 0, s[34:35]
	s_cmpk_lt_u32 s10, 0x7e
	v_lshl_add_u64 v[124:125], v[124:125], 0, s[34:35]
	s_cbranch_scc1 .LBB0_779
; #define LAS __attribute__((address_space(3)))
; template <int DK, int PAR, bool HASNEXT, bool LDK, bool LDV, bool STK> ...
;     ...
;     LAS unsigned char* Kb = lds + ((PAR ^ 1) * A::KBUF);
;     LAS unsigned char* Vb = lds + 2 * A::KBUF + PAR * A::VBUF;
;     __builtin_amdgcn_s_setprio(1);
;     if (LDK) { ldk0 = *(const u32x4*)(kg0 + (size_t)(t + 3) * kstep); if (has1) ldk1 = *(const u32x4*)(kg1 + (size_t)(t + 3) * kstep); }
;     if (LDV) ldv = *(const u32x4*)(vg + (size_t)(t + 2) * vstep);
;     bf16x8 kf[A::NDS][2];
;     if (HASNEXT) {
; #pragma unroll
;         for (int ds = 0; ds < A::NDS; ++ds) {
;             kf[ds][0] = *(const LAS bf16x8*)(Kb + aoffk + ds * 32);
;             kf[ds][1] = *(const LAS bf16x8*)(Kb + aoffk + 32 * A::KSTR + ds * 32);
;         }
;     }
;     s16x4 vlo[4][2], vhi[4][2];
; #pragma unroll
;     for (int j = 0; j < 2; ++j) {
;         vlo[j][0] = vtr(Vb + aoffv + j * 16 * A::VSTR); vhi[j][0] = vtr(Vb + aoffv + (j * 16 + 8) * A::VSTR);
;         vlo[j][1] = vtr(Vb + aoffv + j * 16 * A::VSTR + 64); vhi[j][1] = vtr(Vb + aoffv + (j * 16 + 8) * A::VSTR + 64);
;     }
;     if (HASNEXT) {
;         f32x16 z;
; #pragma unroll
;         for (int i = 0; i < 16; ++i) z[i] = 0.f;
; #pragma unroll
;         for (int ds = 0; ds < A::NDS; ++ds) {
;             N0 = __builtin_amdgcn_mfma_f32_32x32x16_bf16(kf[ds][0], qf[ds], ds == 0 ? z : N0, 0, 0, 0);
;             N1 = __builtin_amdgcn_mfma_f32_32x32x16_bf16(kf[ds][1], qf[ds], ds == 0 ? z : N1, 0, 0, 0);
;         }
;     }
; #pragma unroll
;     for (int i = 0; i < 16; ++i) { l += C0[i]; l += C1[i]; }
;     bf16x8 pb[4];
;     { u32x4 w;
;       w.x = pk2(C0[0], C0[1]); w.y = pk2(C0[2], C0[3]); w.z = pk2(C0[4], C0[5]); w.w = pk2(C0[6], C0[7]); pb[0] = __builtin_bit_cast(bf16x8, w);
;       w.x = pk2(C0[8], C0[9]); w.y = pk2(C0[10], C0[11]); w.z = pk2(C0[12], C0[13]); w.w = pk2(C0[14], C0[15]); pb[1] = __builtin_bit_cast(bf16x8, w);
;       w.x = pk2(C1[0], C1[1]); w.y = pk2(C1[2], C1[3]); w.z = pk2(C1[4], C1[5]); w.w = pk2(C1[6], C1[7]); pb[2] = __builtin_bit_cast(bf16x8, w);
;       w.x = pk2(C1[8], C1[9]); w.y = pk2(C1[10], C1[11]); w.z = pk2(C1[12], C1[13]); w.w = pk2(C1[14], C1[15]); pb[3] = __builtin_bit_cast(bf16x8, w); }
;     if (HASNEXT) {
;         constexpr int VPER = (DK == 64) ? 6 : 4;
; #pragma unroll
	s_waitcnt vmcnt(0)
	ds_read_b128 v[80:83], v130
	s_waitcnt lgkmcnt(0)
	s_setprio 1
	ds_read_b128 v[48:51], v131 offset:17920
	ds_read_b128 v[124:127], v131 offset:17952
	ds_read_b128 v[182:185], v131 offset:13376
	ds_read_b128 v[186:189], v131 offset:17984
	ds_read_b128 v[190:193], v131 offset:13408
	ds_read_b128 v[194:197], v131 offset:18016
	ds_read_b64_tr_b16 v[110:111], v96 offset:26624
	ds_read_b64_tr_b16 v[112:113], v96 offset:28160
	ds_read_b64_tr_b16 v[106:107], v96 offset:26688
	s_waitcnt lgkmcnt(8)
	v_mfma_f32_32x32x16_bf16 v[48:63], v[48:51], v[76:79], 0
	v_add_co_u32_e32 v32, vcc, 0x20c000, v120
	ds_read_b64_tr_b16 v[108:109], v96 offset:28224
	s_nop 0
	v_addc_co_u32_e32 v33, vcc, 0, v121, vcc
	global_load_dwordx4 v[88:91], v[32:33], off
	v_add_co_u32_e32 v32, vcc, 0x208000, v118
	ds_read_b128 v[120:123], v131 offset:13344
	s_nop 0
	v_addc_co_u32_e32 v33, vcc, 0, v119, vcc
	global_load_dwordx4 v[92:95], v[32:33], off
	ds_read_b128 v[32:35], v131 offset:13312
	s_waitcnt lgkmcnt(0)
	v_mfma_f32_32x32x16_bf16 v[32:47], v[32:35], v[76:79], 0
	ds_read_b64_tr_b16 v[102:103], v96 offset:29696
	ds_read_b64_tr_b16 v[104:105], v96 offset:31232
	ds_read_b64_tr_b16 v[98:99], v96 offset:29760
	ds_read_b64_tr_b16 v[100:101], v96 offset:31296
	v_mfma_f32_32x32x16_bf16 v[32:47], v[120:123], v[72:75], v[32:47]
	v_add_f32_e32 v120, v146, v172
	v_add_f32_e32 v120, v132, v120
	v_cvt_pk_bf16_f32 v132, v132, v133
	v_add_f32_e32 v120, v148, v120
	v_add_f32_e32 v120, v133, v120
	v_cvt_pk_bf16_f32 v133, v134, v135
	v_add_f32_e32 v120, v158, v120
	v_add_f32_e32 v120, v134, v120
	v_cvt_pk_bf16_f32 v134, v136, v137
	v_add_f32_e32 v120, v159, v120
	v_add_f32_e32 v120, v135, v120
	v_cvt_pk_bf16_f32 v135, v139, v141
	v_mfma_f32_32x32x16_bf16 v[48:63], v[124:127], v[72:75], v[48:63]
	v_cvt_pk_bf16_f32 v124, v161, v163
	v_cvt_pk_bf16_f32 v125, v165, v168
	v_cvt_pk_bf16_f32 v126, v167, v169
	v_cvt_pk_bf16_f32 v127, v170, v171
	v_add_f32_e32 v120, v160, v120
	v_add_f32_e32 v120, v136, v120
	v_add_f32_e32 v120, v162, v120
	v_add_f32_e32 v120, v137, v120
	v_mfma_f32_32x32x16_bf16 v[32:47], v[182:185], v[68:71], v[32:47]
	v_add_f32_e32 v120, v164, v120
	v_add_f32_e32 v120, v139, v120
	v_add_f32_e32 v120, v166, v120
	v_add_f32_e32 v120, v141, v120
	v_add_f32_e32 v120, v161, v120
	v_add_f32_e32 v120, v138, v120
	v_cvt_pk_bf16_f32 v136, v138, v140
	v_mfma_f32_32x32x16_bf16 v[48:63], v[186:189], v[68:71], v[48:63]
	v_add_f32_e32 v120, v163, v120
	v_add_f32_e32 v120, v140, v120
	v_add_f32_e32 v120, v165, v120
	v_add_f32_e32 v120, v142, v120
	v_add_f32_e32 v120, v168, v120
	v_add_f32_e32 v120, v143, v120
	v_cvt_pk_bf16_f32 v137, v142, v143
	v_mfma_f32_32x32x16_bf16 v[32:47], v[190:193], v[64:67], v[32:47]
	v_add_f32_e32 v120, v167, v120
	v_add_f32_e32 v120, v144, v120
	v_add_f32_e32 v120, v169, v120
	v_add_f32_e32 v120, v145, v120
	v_add_f32_e32 v120, v170, v120
	v_add_f32_e32 v120, v147, v120
	v_cvt_pk_bf16_f32 v138, v144, v145
	v_mfma_f32_32x32x16_bf16 v[48:63], v[194:197], v[64:67], v[48:63]
	v_add_f32_e32 v120, v171, v120
	v_add_f32_e32 v128, v149, v120
	v_cvt_pk_bf16_f32 v120, v146, v148
	v_cvt_pk_bf16_f32 v121, v158, v159
	v_cvt_pk_bf16_f32 v122, v160, v162
	v_cvt_pk_bf16_f32 v123, v164, v166
	v_cvt_pk_bf16_f32 v139, v147, v149
	s_nop 0
	v_mfma_f32_32x32x16_bf16 v[16:31], v[110:113], v[120:123], v[16:31]
	ds_read_b64_tr_b16 v[110:111], v96 offset:32832
	ds_read_b64_tr_b16 v[112:113], v96 offset:34368
	v_exp_f32_e32 v140, v32
	v_exp_f32_e32 v141, v48
	v_exp_f32_e32 v142, v33
	v_exp_f32_e32 v143, v49
	v_exp_f32_e32 v144, v34
	v_mfma_f32_32x32x16_bf16 v[0:15], v[106:109], v[120:123], v[0:15]
	ds_read_b64_tr_b16 v[106:107], v96 offset:32768
	ds_read_b64_tr_b16 v[108:109], v96 offset:34304
	ds_read_b64_tr_b16 v[120:121], v96 offset:35904
	ds_read_b64_tr_b16 v[122:123], v96 offset:37440
	v_exp_f32_e32 v145, v50
	v_exp_f32_e32 v146, v35
	v_exp_f32_e32 v147, v51
	s_waitcnt lgkmcnt(8)
	v_mfma_f32_32x32x16_bf16 v[16:31], v[102:105], v[124:127], v[16:31]
	ds_read_b64_tr_b16 v[102:103], v96 offset:35840
	ds_read_b64_tr_b16 v[104:105], v96 offset:37376
	v_exp_f32_e32 v148, v36
	v_exp_f32_e32 v149, v52
	v_exp_f32_e32 v150, v37
	v_exp_f32_e32 v151, v53
	v_exp_f32_e32 v152, v38
	s_waitcnt lgkmcnt(8)
	v_mfma_f32_32x32x16_bf16 v[0:15], v[98:101], v[124:127], v[0:15]
	v_exp_f32_e32 v153, v54
	v_exp_f32_e32 v154, v39
	v_exp_f32_e32 v155, v55
	v_exp_f32_e32 v158, v40
	v_exp_f32_e32 v159, v58
	v_exp_f32_e32 v160, v43
	v_exp_f32_e32 v161, v59
	s_waitcnt lgkmcnt(4)
	v_mfma_f32_32x32x16_bf16 v[16:31], v[106:109], v[132:135], v[16:31]
	v_exp_f32_e32 v162, v44
	v_exp_f32_e32 v163, v60
	v_exp_f32_e32 v164, v45
	v_exp_f32_e32 v165, v61
	v_exp_f32_e32 v166, v46
	v_exp_f32_e32 v167, v62
	v_exp_f32_e32 v168, v47
	v_mfma_f32_32x32x16_bf16 v[0:15], v[110:113], v[132:135], v[0:15]
	v_exp_f32_e32 v132, v56
	v_exp_f32_e32 v133, v41
	v_exp_f32_e32 v134, v57
	v_exp_f32_e32 v135, v42
	v_exp_f32_e32 v169, v63
	s_waitcnt lgkmcnt(0)
	v_mfma_f32_32x32x16_bf16 v[16:31], v[102:105], v[136:139], v[16:31]
	v_mfma_f32_32x32x16_bf16 v[0:15], v[120:123], v[136:139], v[0:15]
	s_setprio 0
	s_waitcnt vmcnt(3)
	ds_write_b128 v130, v[80:83]
	s_waitcnt vmcnt(2)
	ds_write_b128 v117, v[84:87] offset:38912
	s_waitcnt lgkmcnt(0)
	s_barrier
; #define LAS __attribute__((address_space(3)))
; template <int DK, int PAR, bool HASNEXT, bool LDK, bool LDV, bool STK> ...
;     ...
;     LAS unsigned char* Kb = lds + ((PAR ^ 1) * A::KBUF);
;     LAS unsigned char* Vb = lds + 2 * A::KBUF + PAR * A::VBUF;
;     __builtin_amdgcn_s_setprio(1);
;     if (LDK) { ldk0 = *(const u32x4*)(kg0 + (size_t)(t + 3) * kstep); if (has1) ldk1 = *(const u32x4*)(kg1 + (size_t)(t + 3) * kstep); }
;     if (LDV) ldv = *(const u32x4*)(vg + (size_t)(t + 2) * vstep);
;     bf16x8 kf[A::NDS][2];
;     if (HASNEXT) {
; #pragma unroll
;         for (int ds = 0; ds < A::NDS; ++ds) {
;             kf[ds][0] = *(const LAS bf16x8*)(Kb + aoffk + ds * 32);
;             kf[ds][1] = *(const LAS bf16x8*)(Kb + aoffk + 32 * A::KSTR + ds * 32);
;         }
;     }
;     s16x4 vlo[4][2], vhi[4][2];
; #pragma unroll
;     for (int j = 0; j < 2; ++j) {
;         vlo[j][0] = vtr(Vb + aoffv + j * 16 * A::VSTR); vhi[j][0] = vtr(Vb + aoffv + (j * 16 + 8) * A::VSTR);
;         vlo[j][1] = vtr(Vb + aoffv + j * 16 * A::VSTR + 64); vhi[j][1] = vtr(Vb + aoffv + (j * 16 + 8) * A::VSTR + 64);
;     }
;     if (HASNEXT) {
;         f32x16 z;
; #pragma unroll
;         for (int i = 0; i < 16; ++i) z[i] = 0.f;
; #pragma unroll
;         for (int ds = 0; ds < A::NDS; ++ds) {
;             N0 = __builtin_amdgcn_mfma_f32_32x32x16_bf16(kf[ds][0], qf[ds], ds == 0 ? z : N0, 0, 0, 0);
;             N1 = __builtin_amdgcn_mfma_f32_32x32x16_bf16(kf[ds][1], qf[ds], ds == 0 ? z : N1, 0, 0, 0);
;         }
;     }
; #pragma unroll
;     for (int i = 0; i < 16; ++i) { l += C0[i]; l += C1[i]; }
;     bf16x8 pb[4];
;     { u32x4 w;
;       w.x = pk2(C0[0], C0[1]); w.y = pk2(C0[2], C0[3]); w.z = pk2(C0[4], C0[5]); w.w = pk2(C0[6], C0[7]); pb[0] = __builtin_bit_cast(bf16x8, w);
;       w.x = pk2(C0[8], C0[9]); w.y = pk2(C0[10], C0[11]); w.z = pk2(C0[12], C0[13]); w.w = pk2(C0[14], C0[15]); pb[1] = __builtin_bit_cast(bf16x8, w);
;       w.x = pk2(C1[0], C1[1]); w.y = pk2(C1[2], C1[3]); w.z = pk2(C1[4], C1[5]); w.w = pk2(C1[6], C1[7]); pb[2] = __builtin_bit_cast(bf16x8, w);
;       w.x = pk2(C1[8], C1[9]); w.y = pk2(C1[10], C1[11]); w.z = pk2(C1[12], C1[13]); w.w = pk2(C1[14], C1[15]); pb[3] = __builtin_bit_cast(bf16x8, w); }
;     if (HASNEXT) {
;         constexpr int VPER = (DK == 64) ? 6 : 4;
; #pragma unroll
	s_setprio 1
	ds_read_b128 v[32:35], v131
	s_mov_b32 s8, 0x20c000
	ds_read_b128 v[84:87], v131 offset:32
	ds_read_b128 v[98:101], v131 offset:4640
	ds_read_b128 v[102:105], v131 offset:64
	ds_read_b128 v[106:109], v131 offset:4672
	ds_read_b128 v[110:113], v131 offset:96
	ds_read_b64_tr_b16 v[122:123], v96 offset:38912
	ds_read_b64_tr_b16 v[124:125], v96 offset:40448
	s_waitcnt lgkmcnt(7)
	v_mfma_f32_32x32x16_bf16 v[32:47], v[32:35], v[76:79], 0
	v_add_co_u32_e32 v48, vcc, s8, v118
	v_add_f32_e32 v52, v140, v128
	s_nop 0
	v_addc_co_u32_e32 v49, vcc, 0, v119, vcc
	global_load_dwordx4 v[80:83], v[48:49], off
	ds_read_b128 v[48:51], v131 offset:4608
	v_add_f32_e32 v52, v141, v52
	v_add_f32_e32 v52, v142, v52
	v_add_f32_e32 v128, v143, v52
	s_waitcnt lgkmcnt(0)
	v_mfma_f32_32x32x16_bf16 v[48:63], v[48:51], v[76:79], 0
	v_add_f32_e32 v128, v144, v128
	v_add_f32_e32 v128, v145, v128
	v_add_f32_e32 v128, v146, v128
	v_add_f32_e32 v128, v147, v128
	v_add_f32_e32 v128, v148, v128
	v_add_f32_e32 v136, v149, v128
	ds_read_b128 v[118:121], v131 offset:4704
	v_mfma_f32_32x32x16_bf16 v[32:47], v[84:87], v[72:75], v[32:47]
	v_add_f32_e32 v84, v150, v136
	v_add_f32_e32 v84, v151, v84
	v_add_f32_e32 v84, v152, v84
	v_add_f32_e32 v84, v153, v84
	v_add_f32_e32 v84, v154, v84
	v_add_f32_e32 v86, v155, v84
	ds_read_b64_tr_b16 v[126:127], v96 offset:38976
	v_mfma_f32_32x32x16_bf16 v[48:63], v[98:101], v[72:75], v[48:63]
	v_add_f32_e32 v86, v158, v86
	v_add_f32_e32 v86, v132, v86
	v_add_f32_e32 v86, v133, v86
	v_add_f32_e32 v86, v134, v86
	v_add_f32_e32 v86, v135, v86
	v_add_f32_e32 v98, v159, v86
	ds_read_b64_tr_b16 v[128:129], v96 offset:40512
	v_mfma_f32_32x32x16_bf16 v[32:47], v[102:105], v[68:71], v[32:47]
	v_add_f32_e32 v98, v160, v98
	v_add_f32_e32 v98, v161, v98
	v_add_f32_e32 v98, v162, v98
	v_add_f32_e32 v98, v163, v98
	v_add_f32_e32 v98, v164, v98
	v_add_f32_e32 v100, v165, v98
	ds_read_b64_tr_b16 v[84:85], v96 offset:41984
	v_mfma_f32_32x32x16_bf16 v[48:63], v[106:109], v[68:71], v[48:63]
	v_add_f32_e32 v100, v166, v100
	v_add_f32_e32 v100, v167, v100
	v_add_f32_e32 v100, v168, v100
	ds_read_b64_tr_b16 v[86:87], v96 offset:43520
	ds_read_b64_tr_b16 v[98:99], v96 offset:42048
	v_add_f32_e32 v136, v169, v100
	ds_read_b64_tr_b16 v[100:101], v96 offset:43584
	v_cvt_pk_bf16_f32 v102, v140, v142
	v_cvt_pk_bf16_f32 v103, v144, v146
	v_mfma_f32_32x32x16_bf16 v[32:47], v[110:113], v[64:67], v[32:47]
	v_cvt_pk_bf16_f32 v104, v148, v150
	v_cvt_pk_bf16_f32 v105, v152, v154
	v_cvt_pk_bf16_f32 v106, v158, v133
	v_cvt_pk_bf16_f32 v107, v135, v160
	v_cvt_pk_bf16_f32 v108, v162, v164
	v_cvt_pk_bf16_f32 v109, v166, v168
	s_waitcnt lgkmcnt(6)
	v_mfma_f32_32x32x16_bf16 v[48:63], v[118:121], v[64:67], v[48:63]
	v_cvt_pk_bf16_f32 v110, v141, v143
	v_cvt_pk_bf16_f32 v111, v145, v147
	v_cvt_pk_bf16_f32 v112, v149, v151
	v_cvt_pk_bf16_f32 v113, v153, v155
	v_cvt_pk_bf16_f32 v118, v132, v134
	v_cvt_pk_bf16_f32 v119, v159, v161
	v_cvt_pk_bf16_f32 v120, v163, v165
	v_cvt_pk_bf16_f32 v121, v167, v169
	v_mfma_f32_32x32x16_bf16 v[16:31], v[122:125], v[102:105], v[16:31]
	ds_read_b64_tr_b16 v[122:123], v96 offset:45120
	ds_read_b64_tr_b16 v[124:125], v96 offset:46656
	v_exp_f32_e32 v132, v32
	v_exp_f32_e32 v133, v48
	v_exp_f32_e32 v134, v33
	v_exp_f32_e32 v135, v49
	v_exp_f32_e32 v137, v34
	s_waitcnt lgkmcnt(6)
	v_mfma_f32_32x32x16_bf16 v[0:15], v[126:129], v[102:105], v[0:15]
	ds_read_b64_tr_b16 v[102:103], v96 offset:45056
	ds_read_b64_tr_b16 v[104:105], v96 offset:46592
	ds_read_b64_tr_b16 v[126:127], v96 offset:48192
	ds_read_b64_tr_b16 v[128:129], v96 offset:49728
	v_exp_f32_e32 v138, v50
	v_exp_f32_e32 v139, v35
	v_exp_f32_e32 v140, v51
	s_waitcnt lgkmcnt(8)
	v_mfma_f32_32x32x16_bf16 v[16:31], v[84:87], v[106:109], v[16:31]
	ds_read_b64_tr_b16 v[84:85], v96 offset:48128
	ds_read_b64_tr_b16 v[86:87], v96 offset:49664
	v_exp_f32_e32 v141, v36
	v_exp_f32_e32 v142, v52
	v_exp_f32_e32 v143, v37
	v_exp_f32_e32 v144, v53
	v_exp_f32_e32 v145, v38
	s_waitcnt lgkmcnt(8)
	v_mfma_f32_32x32x16_bf16 v[0:15], v[98:101], v[106:109], v[0:15]
	v_exp_f32_e32 v146, v54
	v_exp_f32_e32 v147, v39
	v_exp_f32_e32 v148, v55
	v_exp_f32_e32 v149, v40
	v_exp_f32_e32 v150, v58
	v_exp_f32_e32 v151, v43
	v_exp_f32_e32 v152, v59
	s_waitcnt lgkmcnt(4)
	v_mfma_f32_32x32x16_bf16 v[16:31], v[102:105], v[110:113], v[16:31]
	v_exp_f32_e32 v153, v44
	v_exp_f32_e32 v154, v60
	v_exp_f32_e32 v155, v45
	v_exp_f32_e32 v158, v61
	v_exp_f32_e32 v159, v46
	v_exp_f32_e32 v160, v62
	v_exp_f32_e32 v161, v47
	v_mfma_f32_32x32x16_bf16 v[0:15], v[122:125], v[110:113], v[0:15]
	v_exp_f32_e32 v122, v56
	v_exp_f32_e32 v123, v41
	v_exp_f32_e32 v124, v57
	v_exp_f32_e32 v125, v42
	v_exp_f32_e32 v162, v63
	s_waitcnt lgkmcnt(0)
	v_mfma_f32_32x32x16_bf16 v[16:31], v[84:87], v[118:121], v[16:31]
	v_mfma_f32_32x32x16_bf16 v[0:15], v[126:129], v[118:121], v[0:15]
	s_setprio 0
	s_waitcnt vmcnt(2)
	ds_write_b128 v130, v[88:91] offset:13312
	s_waitcnt vmcnt(1)
	ds_write_b128 v117, v[92:95] offset:26624
	s_waitcnt lgkmcnt(0)
	s_barrier
; #define LAS __attribute__((address_space(3)))
; template <int DK, int PAR, bool HASNEXT, bool LDK, bool LDV, bool STK> ...
;     ...
;     LAS unsigned char* Kb = lds + ((PAR ^ 1) * A::KBUF);
;     LAS unsigned char* Vb = lds + 2 * A::KBUF + PAR * A::VBUF;
;     __builtin_amdgcn_s_setprio(1);
;     if (LDK) { ldk0 = *(const u32x4*)(kg0 + (size_t)(t + 3) * kstep); if (has1) ldk1 = *(const u32x4*)(kg1 + (size_t)(t + 3) * kstep); }
;     if (LDV) ldv = *(const u32x4*)(vg + (size_t)(t + 2) * vstep);
;     bf16x8 kf[A::NDS][2];
;     if (HASNEXT) {
; #pragma unroll
;         for (int ds = 0; ds < A::NDS; ++ds) {
;             kf[ds][0] = *(const LAS bf16x8*)(Kb + aoffk + ds * 32);
;             kf[ds][1] = *(const LAS bf16x8*)(Kb + aoffk + 32 * A::KSTR + ds * 32);
;         }
;     }
;     s16x4 vlo[4][2], vhi[4][2];
; #pragma unroll
;     for (int j = 0; j < 2; ++j) {
;         vlo[j][0] = vtr(Vb + aoffv + j * 16 * A::VSTR); vhi[j][0] = vtr(Vb + aoffv + (j * 16 + 8) * A::VSTR);
;         vlo[j][1] = vtr(Vb + aoffv + j * 16 * A::VSTR + 64); vhi[j][1] = vtr(Vb + aoffv + (j * 16 + 8) * A::VSTR + 64);
;     }
;     if (HASNEXT) {
;         f32x16 z;
; #pragma unroll
;         for (int i = 0; i < 16; ++i) z[i] = 0.f;
; #pragma unroll
;         for (int ds = 0; ds < A::NDS; ++ds) {
;             N0 = __builtin_amdgcn_mfma_f32_32x32x16_bf16(kf[ds][0], qf[ds], ds == 0 ? z : N0, 0, 0, 0);
;             N1 = __builtin_amdgcn_mfma_f32_32x32x16_bf16(kf[ds][1], qf[ds], ds == 0 ? z : N1, 0, 0, 0);
;         }
;     }
; #pragma unroll
;     for (int i = 0; i < 16; ++i) { l += C0[i]; l += C1[i]; }
;     bf16x8 pb[4];
;     { u32x4 w;
;       w.x = pk2(C0[0], C0[1]); w.y = pk2(C0[2], C0[3]); w.z = pk2(C0[4], C0[5]); w.w = pk2(C0[6], C0[7]); pb[0] = __builtin_bit_cast(bf16x8, w);
;       w.x = pk2(C0[8], C0[9]); w.y = pk2(C0[10], C0[11]); w.z = pk2(C0[12], C0[13]); w.w = pk2(C0[14], C0[15]); pb[1] = __builtin_bit_cast(bf16x8, w);
;       w.x = pk2(C1[0], C1[1]); w.y = pk2(C1[2], C1[3]); w.z = pk2(C1[4], C1[5]); w.w = pk2(C1[6], C1[7]); pb[2] = __builtin_bit_cast(bf16x8, w);
;       w.x = pk2(C1[8], C1[9]); w.y = pk2(C1[10], C1[11]); w.z = pk2(C1[12], C1[13]); w.w = pk2(C1[14], C1[15]); pb[3] = __builtin_bit_cast(bf16x8, w); }
;     if (HASNEXT) {
;         constexpr int VPER = (DK == 64) ? 6 : 4;
; #pragma unroll
	s_setprio 1
	ds_read_b128 v[32:35], v131 offset:13312
	ds_read_b128 v[48:51], v131 offset:17920
	ds_read_b128 v[84:87], v131 offset:13344
	ds_read_b128 v[88:91], v131 offset:17952
	ds_read_b128 v[92:95], v131 offset:13376
	ds_read_b128 v[98:101], v131 offset:17984
	ds_read_b128 v[102:105], v131 offset:13408
	ds_read_b128 v[106:109], v131 offset:18016
	ds_read_b64_tr_b16 v[110:111], v96 offset:26624
	s_waitcnt lgkmcnt(8)
	v_mfma_f32_32x32x16_bf16 v[32:47], v[32:35], v[76:79], 0
	v_add_f32_e32 v52, v132, v136
	v_add_f32_e32 v52, v133, v52
	v_add_f32_e32 v52, v134, v52
	v_add_f32_e32 v52, v135, v52
	v_add_f32_e32 v52, v137, v52
	v_add_f32_e32 v118, v138, v52
	ds_read_b64_tr_b16 v[112:113], v96 offset:28160
	s_waitcnt lgkmcnt(8)
	v_mfma_f32_32x32x16_bf16 v[48:63], v[48:51], v[76:79], 0
	v_add_f32_e32 v78, v139, v118
	v_add_f32_e32 v78, v140, v78
	v_add_f32_e32 v78, v141, v78
	v_add_f32_e32 v78, v142, v78
	v_add_f32_e32 v78, v143, v78
	v_add_f32_e32 v118, v144, v78
	ds_read_b64_tr_b16 v[76:77], v96 offset:26688
	s_waitcnt lgkmcnt(8)
	v_mfma_f32_32x32x16_bf16 v[32:47], v[84:87], v[72:75], v[32:47]
	v_add_f32_e32 v84, v145, v118
	v_add_f32_e32 v84, v146, v84
	v_add_f32_e32 v84, v147, v84
	v_add_f32_e32 v84, v148, v84
	v_add_f32_e32 v84, v149, v84
	v_add_f32_e32 v84, v122, v84
	ds_read_b64_tr_b16 v[78:79], v96 offset:28224
	s_waitcnt lgkmcnt(8)
	v_mfma_f32_32x32x16_bf16 v[48:63], v[88:91], v[72:75], v[48:63]
	v_add_f32_e32 v74, v123, v84
	v_add_f32_e32 v74, v124, v74
	v_add_f32_e32 v74, v125, v74
	v_add_f32_e32 v74, v150, v74
	v_add_f32_e32 v74, v151, v74
	v_add_f32_e32 v84, v152, v74
	ds_read_b64_tr_b16 v[72:73], v96 offset:29696
	s_waitcnt lgkmcnt(8)
	v_mfma_f32_32x32x16_bf16 v[32:47], v[92:95], v[68:71], v[32:47]
	v_add_f32_e32 v84, v153, v84
	v_add_f32_e32 v84, v154, v84
	v_add_f32_e32 v84, v155, v84
	v_add_f32_e32 v84, v158, v84
	v_add_f32_e32 v84, v159, v84
	v_add_f32_e32 v84, v160, v84
	ds_read_b64_tr_b16 v[74:75], v96 offset:31232
	s_waitcnt lgkmcnt(8)
	v_mfma_f32_32x32x16_bf16 v[48:63], v[98:101], v[68:71], v[48:63]
	v_add_f32_e32 v70, v161, v84
	ds_read_b64_tr_b16 v[68:69], v96 offset:29760
	v_add_f32_e32 v118, v162, v70
	ds_read_b64_tr_b16 v[70:71], v96 offset:31296
	v_cvt_pk_bf16_f32 v84, v132, v134
	v_cvt_pk_bf16_f32 v85, v137, v139
	v_cvt_pk_bf16_f32 v86, v141, v143
	v_cvt_pk_bf16_f32 v87, v145, v147
	s_waitcnt lgkmcnt(9)
	v_mfma_f32_32x32x16_bf16 v[32:47], v[102:105], v[64:67], v[32:47]
	v_cvt_pk_bf16_f32 v88, v149, v123
	v_cvt_pk_bf16_f32 v89, v125, v151
	v_cvt_pk_bf16_f32 v90, v153, v155
	v_cvt_pk_bf16_f32 v91, v159, v161
	v_cvt_pk_bf16_f32 v92, v133, v135
	v_cvt_pk_bf16_f32 v93, v138, v140
	s_waitcnt lgkmcnt(8)
	v_mfma_f32_32x32x16_bf16 v[48:63], v[106:109], v[64:67], v[48:63]
	v_cvt_pk_bf16_f32 v94, v142, v144
	v_cvt_pk_bf16_f32 v95, v146, v148
	v_cvt_pk_bf16_f32 v64, v122, v124
	v_cvt_pk_bf16_f32 v65, v150, v152
	v_cvt_pk_bf16_f32 v66, v154, v158
	v_cvt_pk_bf16_f32 v67, v160, v162
	s_waitcnt lgkmcnt(6)
	v_mfma_f32_32x32x16_bf16 v[16:31], v[110:113], v[84:87], v[16:31]
	ds_read_b64_tr_b16 v[98:99], v96 offset:35904
	ds_read_b64_tr_b16 v[100:101], v96 offset:37440
	v_exp_f32_e32 v102, v32
	s_nop 0
	v_exp_f32_e32 v103, v48
	v_exp_f32_e32 v48, v33
	v_exp_f32_e32 v63, v63
	s_waitcnt lgkmcnt(6)
	v_mfma_f32_32x32x16_bf16 v[0:15], v[76:79], v[84:87], v[0:15]
	ds_read_b64_tr_b16 v[76:77], v96 offset:32768
	ds_read_b64_tr_b16 v[78:79], v96 offset:34304
	ds_read_b64_tr_b16 v[84:85], v96 offset:32832
	ds_read_b64_tr_b16 v[86:87], v96 offset:34368
	s_waitcnt lgkmcnt(8)
	v_mfma_f32_32x32x16_bf16 v[16:31], v[72:75], v[88:91], v[16:31]
	ds_read_b64_tr_b16 v[72:73], v96 offset:35840
	ds_read_b64_tr_b16 v[74:75], v96 offset:37376
	s_waitcnt lgkmcnt(8)
	v_mfma_f32_32x32x16_bf16 v[0:15], v[68:71], v[88:91], v[0:15]
	v_exp_f32_e32 v68, v49
	v_exp_f32_e32 v49, v34
	v_exp_f32_e32 v69, v50
	v_exp_f32_e32 v50, v35
	v_exp_f32_e32 v70, v51
	v_exp_f32_e32 v51, v36
	v_exp_f32_e32 v71, v52
	s_waitcnt lgkmcnt(4)
	v_mfma_f32_32x32x16_bf16 v[16:31], v[76:79], v[92:95], v[16:31]
	v_exp_f32_e32 v52, v37
	v_exp_f32_e32 v76, v53
	v_exp_f32_e32 v53, v38
	v_exp_f32_e32 v77, v54
	v_exp_f32_e32 v54, v39
	v_exp_f32_e32 v78, v55
	v_exp_f32_e32 v55, v40
	s_waitcnt lgkmcnt(2)
	v_mfma_f32_32x32x16_bf16 v[0:15], v[84:87], v[92:95], v[0:15]
	v_exp_f32_e32 v79, v56
	v_exp_f32_e32 v56, v41
	v_exp_f32_e32 v84, v57
	v_exp_f32_e32 v57, v42
	v_exp_f32_e32 v85, v58
	v_exp_f32_e32 v58, v43
	v_exp_f32_e32 v86, v59
	s_waitcnt lgkmcnt(0)
	v_mfma_f32_32x32x16_bf16 v[16:31], v[72:75], v[64:67], v[16:31]
	v_exp_f32_e32 v59, v44
	v_exp_f32_e32 v72, v60
	v_exp_f32_e32 v60, v45
	v_exp_f32_e32 v73, v61
	v_exp_f32_e32 v61, v46
	v_exp_f32_e32 v74, v62
	v_exp_f32_e32 v62, v47
	v_mfma_f32_32x32x16_bf16 v[0:15], v[98:101], v[64:67], v[0:15]
	s_setprio 0
	s_waitcnt vmcnt(0)
	ds_write_b128 v117, v[80:83] offset:38912
	s_waitcnt lgkmcnt(0)
	s_barrier
; template <int DK, int PAR, bool HASNEXT, bool LDK, bool LDV, bool STK> ...
;     ...
; #pragma unroll
;     for (int i = 0; i < 16; ++i) { l += C0[i]; l += C1[i]; }
;     bf16x8 pb[4];
;     { u32x4 w;
;       w.x = pk2(C0[0], C0[1]); w.y = pk2(C0[2], C0[3]); w.z = pk2(C0[4], C0[5]); w.w = pk2(C0[6], C0[7]); pb[0] = __builtin_bit_cast(bf16x8, w);
;       w.x = pk2(C0[8], C0[9]); w.y = pk2(C0[10], C0[11]); w.z = pk2(C0[12], C0[13]); w.w = pk2(C0[14], C0[15]); pb[1] = __builtin_bit_cast(bf16x8, w);
;       w.x = pk2(C1[0], C1[1]); w.y = pk2(C1[2], C1[3]); w.z = pk2(C1[4], C1[5]); w.w = pk2(C1[6], C1[7]); pb[2] = __builtin_bit_cast(bf16x8, w);
;       w.x = pk2(C1[8], C1[9]); w.y = pk2(C1[10], C1[11]); w.z = pk2(C1[12], C1[13]); w.w = pk2(C1[14], C1[15]); pb[3] = __builtin_bit_cast(bf16x8, w); }
;     if (HASNEXT) {
;         constexpr int VPER = (DK == 64) ? 6 : 4;
; #pragma unroll
;         for (int g = 0; g < 2 * A::NDS; ++g) { __builtin_amdgcn_sched_group_barrier(0x008, 1, 0); __builtin_amdgcn_sched_group_barrier(0x002, VPER, 0); }
;     }
;     asm volatile("" : "+v"(l));
;     __builtin_amdgcn_sched_barrier(0);
; #pragma unroll
;     for (int j = 2; j < 4; ++j) {
;         vlo[j][0] = vtr(Vb + aoffv + j * 16 * A::VSTR); vhi[j][0] = vtr(Vb + aoffv + (j * 16 + 8) * A::VSTR);
;         vlo[j][1] = vtr(Vb + aoffv + j * 16 * A::VSTR + 64); vhi[j][1] = vtr(Vb + aoffv + (j * 16 + 8) * A::VSTR + 64);
;     }
; #pragma unroll
;     for (int j = 0; j < 4; ++j) {
;         const bf16x8 a0 = __builtin_shufflevector(vlo[j][0], vhi[j][0], 0, 1, 2, 3, 4, 5, 6, 7);
;         const bf16x8 a1 = __builtin_shufflevector(vlo[j][1], vhi[j][1], 0, 1, 2, 3, 4, 5, 6, 7);
;         o0 = __builtin_amdgcn_mfma_f32_32x32x16_bf16(a0, pb[j], o0, 0, 0, 0);
;         o1 = __builtin_amdgcn_mfma_f32_32x32x16_bf16(a1, pb[j], o1, 0, 0, 0);
;     }
;     if (HASNEXT) {
; #pragma unroll
;         for (int i = 0; i < 16; ++i) { N0[i] = __builtin_amdgcn_exp2f(N0[i]); N1[i] = __builtin_amdgcn_exp2f(N1[i]); }
; #pragma unroll
;         for (int g = 0; g < 8; ++g) { __builtin_amdgcn_sched_group_barrier(0x008, 1, 0); __builtin_amdgcn_sched_group_barrier(0x002, 4, 0); }
;     }
;     __builtin_amdgcn_sched_barrier(0);
;     __builtin_amdgcn_s_setprio(0);
;     if (STK) { LAS unsigned char* Kn = lds + PAR * A::KBUF; *(LAS u32x4*)(Kn + kl0) = stk0; if (has1) *(LAS u32x4*)(Kn + kl1) = stk1; }
	s_setprio 1
	v_add_f32_e32 v64, v102, v118
	v_add_f32_e32 v64, v103, v64
	v_add_f32_e32 v64, v48, v64
	v_add_f32_e32 v64, v68, v64
	v_add_f32_e32 v64, v49, v64
	v_add_f32_e32 v64, v69, v64
	v_add_f32_e32 v64, v50, v64
	v_add_f32_e32 v64, v70, v64
	v_add_f32_e32 v64, v51, v64
	v_add_f32_e32 v64, v71, v64
	v_add_f32_e32 v64, v52, v64
	v_add_f32_e32 v64, v76, v64
	v_add_f32_e32 v64, v53, v64
	v_add_f32_e32 v64, v77, v64
	v_add_f32_e32 v64, v54, v64
	v_add_f32_e32 v64, v78, v64
	v_add_f32_e32 v64, v55, v64
	v_add_f32_e32 v64, v79, v64
	v_add_f32_e32 v64, v56, v64
	v_add_f32_e32 v64, v84, v64
	v_add_f32_e32 v64, v57, v64
	v_add_f32_e32 v64, v85, v64
	v_add_f32_e32 v64, v58, v64
	v_add_f32_e32 v64, v86, v64
	v_add_f32_e32 v64, v59, v64
	v_add_f32_e32 v64, v72, v64
	v_add_f32_e32 v64, v60, v64
	v_add_f32_e32 v64, v73, v64
	ds_read_b64_tr_b16 v[32:33], v96 offset:38912
	ds_read_b64_tr_b16 v[34:35], v96 offset:40448
	ds_read_b64_tr_b16 v[38:39], v96 offset:40512
	ds_read_b64_tr_b16 v[36:37], v96 offset:38976
	ds_read_b64_tr_b16 v[40:41], v96 offset:41984
	ds_read_b64_tr_b16 v[42:43], v96 offset:43520
	ds_read_b64_tr_b16 v[46:47], v96 offset:43584
	ds_read_b64_tr_b16 v[44:45], v96 offset:42048
	v_add_f32_e32 v64, v61, v64
	v_add_f32_e32 v64, v74, v64
	v_add_f32_e32 v64, v62, v64
	v_add_f32_e32 v64, v63, v64
	v_cvt_pk_bf16_f32 v48, v102, v48
	v_cvt_pk_bf16_f32 v49, v49, v50
	v_cvt_pk_bf16_f32 v50, v51, v52
	v_cvt_pk_bf16_f32 v51, v53, v54
	v_cvt_pk_bf16_f32 v52, v55, v56
	v_cvt_pk_bf16_f32 v53, v57, v58
	v_cvt_pk_bf16_f32 v54, v59, v60
	v_cvt_pk_bf16_f32 v55, v61, v62
	v_cvt_pk_bf16_f32 v56, v103, v68
	v_cvt_pk_bf16_f32 v57, v69, v70
	v_cvt_pk_bf16_f32 v58, v71, v76
	v_cvt_pk_bf16_f32 v59, v77, v78
	v_cvt_pk_bf16_f32 v60, v79, v84
	v_cvt_pk_bf16_f32 v61, v85, v86
	v_cvt_pk_bf16_f32 v62, v72, v73
	v_cvt_pk_bf16_f32 v63, v74, v63
	s_waitcnt lgkmcnt(6)
	v_mfma_f32_32x32x16_bf16 v[16:31], v[32:35], v[48:51], v[16:31]
	ds_read_b64_tr_b16 v[32:33], v96 offset:45056
	ds_read_b64_tr_b16 v[34:35], v96 offset:46592
	s_waitcnt lgkmcnt(6)
	v_mfma_f32_32x32x16_bf16 v[0:15], v[36:39], v[48:51], v[0:15]
	ds_read_b64_tr_b16 v[38:39], v96 offset:46656
	ds_read_b64_tr_b16 v[36:37], v96 offset:45120
	s_waitcnt lgkmcnt(6)
	v_mfma_f32_32x32x16_bf16 v[16:31], v[40:43], v[52:55], v[16:31]
	s_waitcnt lgkmcnt(4)
	v_mfma_f32_32x32x16_bf16 v[0:15], v[44:47], v[52:55], v[0:15]
	s_waitcnt lgkmcnt(2)
	v_mfma_f32_32x32x16_bf16 v[16:31], v[32:35], v[56:59], v[16:31]
	ds_read_b64_tr_b16 v[32:33], v96 offset:48128
	ds_read_b64_tr_b16 v[34:35], v96 offset:49664
	s_waitcnt lgkmcnt(2)
	v_mfma_f32_32x32x16_bf16 v[0:15], v[36:39], v[56:59], v[0:15]
	ds_read_b64_tr_b16 v[38:39], v96 offset:49728
	ds_read_b64_tr_b16 v[36:37], v96 offset:48192
	s_waitcnt lgkmcnt(2)
	v_mfma_f32_32x32x16_bf16 v[16:31], v[32:35], v[60:63], v[16:31]
	s_waitcnt lgkmcnt(0)
	v_mfma_f32_32x32x16_bf16 v[0:15], v[36:39], v[60:63], v[0:15]
	s_setprio 0
	v_mov_b32_e32 v32, v64
	s_nop 1
	v_permlane32_swap_b32_e32 v64, v32
	v_add_f32_e32 v32, v64, v32
	v_div_scale_f32 v33, s[8:9], v32, v32, 1.0
	v_rcp_f32_e32 v34, v33
	v_lshlrev_b32_e32 v96, 1, v116
	s_waitcnt lgkmcnt(0)
	s_barrier
	v_fma_f32 v35, -v33, v34, 1.0
	v_fmac_f32_e32 v34, v35, v34
	v_div_scale_f32 v35, vcc, 1.0, v32, 1.0
	v_mul_f32_e32 v36, v35, v34
	v_fma_f32 v37, -v33, v36, v35
	v_fmac_f32_e32 v36, v37, v34
	v_fma_f32 v33, -v33, v36, v35
	v_div_fmas_f32 v33, v33, v34, v36
	v_div_fixup_f32 v32, v33, v32, 1.0
	v_pk_mul_f32 v[16:17], v[16:17], v[32:33] op_sel_hi:[1,0]
	v_pk_mul_f32 v[18:19], v[18:19], v[32:33] op_sel_hi:[1,0]
	v_pk_mul_f32 v[0:1], v[0:1], v[32:33] op_sel_hi:[1,0]
	v_pk_mul_f32 v[2:3], v[2:3], v[32:33] op_sel_hi:[1,0]
	v_lshlrev_b64 v[34:35], 11, v[114:115]
	v_cvt_pk_bf16_f32 v16, v16, v17
	v_cvt_pk_bf16_f32 v17, v18, v19
	v_pk_mul_f32 v[18:19], v[20:21], v[32:33] op_sel_hi:[1,0]
	v_pk_mul_f32 v[20:21], v[22:23], v[32:33] op_sel_hi:[1,0]
	v_cvt_pk_bf16_f32 v0, v0, v1
	v_cvt_pk_bf16_f32 v1, v2, v3
	v_pk_mul_f32 v[2:3], v[4:5], v[32:33] op_sel_hi:[1,0]
	v_pk_mul_f32 v[4:5], v[6:7], v[32:33] op_sel_hi:[1,0]
	v_lshl_add_u64 v[34:35], s[6:7], 0, v[34:35]
	v_cvt_pk_bf16_f32 v18, v18, v19
	v_cvt_pk_bf16_f32 v19, v20, v21
	v_cvt_pk_bf16_f32 v2, v2, v3
	v_cvt_pk_bf16_f32 v3, v4, v5
	v_lshl_add_u64 v[34:35], v[34:35], 0, v[96:97]
	v_permlane32_swap_b32_e32 v16, v18
	v_permlane32_swap_b32_e32 v17, v19
	v_permlane32_swap_b32_e32 v0, v2
	v_permlane32_swap_b32_e32 v1, v3
	global_store_dwordx4 v[34:35], v[16:19], off
	global_store_dwordx4 v[34:35], v[0:3], off offset:64
	v_pk_mul_f32 v[20:21], v[30:31], v[32:33] op_sel_hi:[1,0]
	v_pk_mul_f32 v[16:17], v[24:25], v[32:33] op_sel_hi:[1,0]
	v_pk_mul_f32 v[18:19], v[26:27], v[32:33] op_sel_hi:[1,0]
	v_pk_mul_f32 v[0:1], v[8:9], v[32:33] op_sel_hi:[1,0]
	v_pk_mul_f32 v[2:3], v[10:11], v[32:33] op_sel_hi:[1,0]
	v_cvt_pk_bf16_f32 v16, v16, v17
	v_cvt_pk_bf16_f32 v17, v18, v19
	v_pk_mul_f32 v[18:19], v[28:29], v[32:33] op_sel_hi:[1,0]
	v_cvt_pk_bf16_f32 v0, v0, v1
	v_cvt_pk_bf16_f32 v1, v2, v3
	v_pk_mul_f32 v[2:3], v[12:13], v[32:33] op_sel_hi:[1,0]
	v_pk_mul_f32 v[4:5], v[14:15], v[32:33] op_sel_hi:[1,0]
	v_cvt_pk_bf16_f32 v18, v18, v19
	v_cvt_pk_bf16_f32 v19, v20, v21
	v_cvt_pk_bf16_f32 v2, v2, v3
	v_cvt_pk_bf16_f32 v3, v4, v5
	v_permlane32_swap_b32_e32 v16, v18
	v_permlane32_swap_b32_e32 v17, v19
	v_permlane32_swap_b32_e32 v0, v2
	v_permlane32_swap_b32_e32 v1, v3
	global_store_dwordx4 v[34:35], v[16:19], off offset:32
	global_store_dwordx4 v[34:35], v[0:3], off offset:96
	s_branch .LBB0_740
